# G1 epilogue stores: write-through without the nt streaming hint
# baseline (speedup 1.0000x reference)
.LBB0_271:
	s_lshl_b32 s0, s3, 8
	v_readlane_b32 s12, v252, 26
	v_add_u32_e32 v174, s0, v155
	s_add_i32 s0, s0, s12
	s_cmp_lt_i32 s0, 0x8000
	s_movk_i32 s1, 0xf800
	s_cselect_b32 s1, s1, 0x7fffe000
	s_cselect_b32 s20, 11, 13
	s_and_b32 s0, s1, s0
	s_sub_i32 s3, s0, s12
	s_add_i32 s21, s83, -5
	s_add_i32 s4, s83, -10
	s_cmp_lt_i32 s83, 10
	s_cselect_b32 s0, s21, s4
	s_cmp_eq_u32 s0, 2
	s_cselect_b32 s1, 4, 0
	s_cmp_lg_u32 s0, 1
	s_cselect_b32 s82, s1, 2
	s_cmp_gt_i32 s83, 9
	s_mov_b64 s[0:1], -1
	v_readlane_b32 s13, v252, 27
	s_cbranch_scc0 .LBB0_278
	s_cmp_gt_u32 s83, 14
	s_cbranch_scc0 .LBB0_274
	v_lshl_add_u32 v176, s83, 7, v190
	v_mov_b32_e32 v177, v0
	v_readlane_b32 s0, v252, 29
	v_lshlrev_b64 v[130:131], 2, v[176:177]
	v_readlane_b32 s1, v252, 30
	v_ashrrev_i32_e32 v175, 31, v174
	v_lshlrev_b64 v[178:179], 12, v[174:175]
	v_lshl_add_u64 v[132:133], s[0:1], 0, v[130:131]
	v_readlane_b32 s0, v252, 38
	v_readlane_b32 s1, v252, 39
	v_lshl_add_u64 v[188:189], s[10:11], 0, v[178:179]
	s_nop 0
	v_lshl_add_u64 v[138:139], s[0:1], 0, v[130:131]
	global_load_dwordx4 v[134:137], v[132:133], off offset:16
	global_load_dwordx4 v[142:145], v[132:133], off
	s_nop 0
	global_load_dwordx4 v[130:133], v[138:139], off offset:16
	s_nop 0
	global_load_dwordx4 v[138:141], v[138:139], off
	s_mov_b64 s[0:1], 0x80000
	s_waitcnt vmcnt(0)
	v_add_f32_e32 v175, v126, v142
	v_mul_f32_e32 v175, 0xbfb8aa3b, v175
	v_exp_f32_e32 v178, v175
	v_add_f32_e32 v175, v118, v138
	v_mul_f32_e32 v175, 0xbfb8aa3b, v175
	v_exp_f32_e32 v175, v175
	v_add_f32_e32 v183, v121, v141
	v_mul_f32_e32 v183, 0xbfb8aa3b, v183
	v_exp_f32_e32 v183, v183
	v_add_f32_e32 v175, 1.0, v175
	v_rcp_f32_e32 v180, v175
	v_add_f32_e32 v175, v127, v143
	v_mul_f32_e32 v175, 0xbfb8aa3b, v175
	v_exp_f32_e32 v179, v175
	v_add_f32_e32 v175, v119, v139
	v_mul_f32_e32 v175, 0xbfb8aa3b, v175
	v_exp_f32_e32 v175, v175
	v_pk_add_f32 v[178:179], v[178:179], 1.0 op_sel_hi:[1,0]
	v_add_f32_e32 v183, 1.0, v183
	v_rcp_f32_e32 v193, v179
	v_add_f32_e32 v175, 1.0, v175
	v_rcp_f32_e32 v181, v175
	v_rcp_f32_e32 v175, v178
	v_rcp_f32_e32 v183, v183
	v_add_f32_e32 v185, v115, v131
	v_pk_mul_f32 v[180:181], v[178:179], v[180:181]
	v_add_f32_e32 v179, v120, v140
	v_mul_f32_e32 v179, 0xbfb8aa3b, v179
	v_exp_f32_e32 v179, v179
	v_add_f32_e32 v178, v128, v144
	v_mul_f32_e32 v178, 0xbfb8aa3b, v178
	v_exp_f32_e32 v178, v178
	v_add_f32_e32 v179, 1.0, v179
	v_rcp_f32_e32 v182, v179
	v_add_f32_e32 v179, v129, v145
	v_mul_f32_e32 v179, 0xbfb8aa3b, v179
	v_exp_f32_e32 v179, v179
	v_mul_f32_e32 v185, 0xbfb8aa3b, v185
	v_exp_f32_e32 v185, v185
	v_add_f32_e32 v187, v117, v133
	v_pk_add_f32 v[178:179], v[178:179], 1.0 op_sel_hi:[1,0]
	v_mul_f32_e32 v187, 0xbfb8aa3b, v187
	v_rcp_f32_e32 v195, v179
	v_pk_mul_f32 v[182:183], v[178:179], v[182:183]
	v_add_f32_e32 v179, v114, v130
	v_mul_f32_e32 v179, 0xbfb8aa3b, v179
	v_exp_f32_e32 v179, v179
	v_rcp_f32_e32 v194, v178
	v_add_f32_e32 v178, v122, v134
	v_mul_f32_e32 v178, 0xbfb8aa3b, v178
	v_add_f32_e32 v179, 1.0, v179
	v_rcp_f32_e32 v184, v179
	v_add_f32_e32 v179, v123, v135
	v_mul_f32_e32 v179, 0xbfb8aa3b, v179
	v_exp_f32_e32 v178, v178
	v_exp_f32_e32 v179, v179
	v_add_f32_e32 v185, 1.0, v185
	v_rcp_f32_e32 v185, v185
	v_exp_f32_e32 v187, v187
	v_pk_add_f32 v[178:179], v[178:179], 1.0 op_sel_hi:[1,0]
	v_cvt_pk_bf16_f32 v208, v175, v193
	v_rcp_f32_e32 v197, v179
	v_pk_mul_f32 v[184:185], v[178:179], v[184:185]
	v_add_f32_e32 v179, v116, v132
	v_mul_f32_e32 v179, 0xbfb8aa3b, v179
	v_exp_f32_e32 v179, v179
	v_rcp_f32_e32 v196, v178
	v_add_f32_e32 v178, v124, v136
	v_mul_f32_e32 v178, 0xbfb8aa3b, v178
	v_add_f32_e32 v179, 1.0, v179
	v_rcp_f32_e32 v186, v179
	v_add_f32_e32 v179, v125, v137
	v_mul_f32_e32 v179, 0xbfb8aa3b, v179
	v_exp_f32_e32 v178, v178
	v_exp_f32_e32 v179, v179
	v_add_f32_e32 v187, 1.0, v187
	v_rcp_f32_e32 v187, v187
	v_add_f32_e32 v175, v110, v142
	v_pk_add_f32 v[178:179], v[178:179], 1.0 op_sel_hi:[1,0]
	v_cvt_pk_bf16_f32 v180, v180, v181
	v_rcp_f32_e32 v198, v178
	v_pk_mul_f32 v[186:187], v[178:179], v[186:187]
	v_rcp_f32_e32 v199, v179
	v_lshlrev_b64 v[178:179], 1, v[176:177]
	v_lshl_add_u64 v[176:177], v[188:189], 0, v[178:179]
	v_cvt_pk_bf16_f32 v181, v182, v183
	v_cvt_pk_bf16_f32 v182, v184, v185
	v_cvt_pk_bf16_f32 v183, v186, v187
	v_mul_f32_e32 v175, 0xbfb8aa3b, v175
	global_store_dwordx4 v[176:177], v[180:183], off offset:2048 sc1
	v_add_f32_e32 v187, v105, v141
	v_mul_f32_e32 v187, 0xbfb8aa3b, v187
	v_exp_f32_e32 v182, v175
	v_add_f32_e32 v175, v102, v138
	v_mul_f32_e32 v175, 0xbfb8aa3b, v175
	v_exp_f32_e32 v175, v175
	v_exp_f32_e32 v187, v187
	v_cvt_pk_bf16_f32 v211, v198, v199
	v_add_f32_e32 v189, v99, v131
	v_add_f32_e32 v175, 1.0, v175
	v_rcp_f32_e32 v184, v175
	v_add_f32_e32 v175, v111, v143
	v_mul_f32_e32 v175, 0xbfb8aa3b, v175
	v_exp_f32_e32 v183, v175
	v_add_f32_e32 v175, v103, v139
	v_mul_f32_e32 v175, 0xbfb8aa3b, v175
	v_exp_f32_e32 v175, v175
	v_pk_add_f32 v[182:183], v[182:183], 1.0 op_sel_hi:[1,0]
	v_add_f32_e32 v187, 1.0, v187
	v_rcp_f32_e32 v193, v183
	v_add_f32_e32 v175, 1.0, v175
	v_rcp_f32_e32 v185, v175
	v_rcp_f32_e32 v175, v182
	v_rcp_f32_e32 v187, v187
	v_mul_f32_e32 v189, 0xbfb8aa3b, v189
	v_pk_mul_f32 v[184:185], v[182:183], v[184:185]
	v_add_f32_e32 v183, v104, v140
	v_mul_f32_e32 v183, 0xbfb8aa3b, v183
	v_exp_f32_e32 v183, v183
	v_add_f32_e32 v182, v112, v144
	v_mul_f32_e32 v182, 0xbfb8aa3b, v182
	v_exp_f32_e32 v182, v182
	v_add_f32_e32 v183, 1.0, v183
	v_rcp_f32_e32 v186, v183
	v_add_f32_e32 v183, v113, v145
	v_mul_f32_e32 v183, 0xbfb8aa3b, v183
	v_exp_f32_e32 v183, v183
	v_exp_f32_e32 v189, v189
	v_cvt_pk_bf16_f32 v209, v194, v195
	v_cvt_pk_bf16_f32 v210, v196, v197
	v_pk_add_f32 v[182:183], v[182:183], 1.0 op_sel_hi:[1,0]
	v_add_f32_e32 v189, 1.0, v189
	v_pk_mul_f32 v[186:187], v[182:183], v[186:187]
	v_rcp_f32_e32 v199, v183
	v_add_f32_e32 v183, v98, v130
	v_mul_f32_e32 v183, 0xbfb8aa3b, v183
	v_exp_f32_e32 v183, v183
	v_rcp_f32_e32 v198, v182
	v_add_f32_e32 v182, v106, v134
	v_mul_f32_e32 v182, 0xbfb8aa3b, v182
	v_add_f32_e32 v183, 1.0, v183
	v_rcp_f32_e32 v188, v183
	v_add_f32_e32 v183, v107, v135
	v_mul_f32_e32 v183, 0xbfb8aa3b, v183
	v_exp_f32_e32 v182, v182
	v_exp_f32_e32 v183, v183
	v_rcp_f32_e32 v189, v189
	global_store_dwordx4 v[176:177], v[208:211], off sc1
	v_add_f32_e32 v195, v101, v133
	v_pk_add_f32 v[182:183], v[182:183], 1.0 op_sel_hi:[1,0]
	v_mul_f32_e32 v195, 0xbfb8aa3b, v195
	v_pk_mul_f32 v[188:189], v[182:183], v[188:189]
	v_rcp_f32_e32 v209, v183
	v_add_f32_e32 v183, v100, v132
	v_mul_f32_e32 v183, 0xbfb8aa3b, v183
	v_exp_f32_e32 v183, v183
	v_exp_f32_e32 v195, v195
	v_rcp_f32_e32 v208, v182
	v_add_f32_e32 v182, v108, v136
	v_add_f32_e32 v183, 1.0, v183
	v_rcp_f32_e32 v194, v183
	v_add_f32_e32 v183, v109, v137
	v_mul_f32_e32 v182, 0xbfb8aa3b, v182
	v_mul_f32_e32 v183, 0xbfb8aa3b, v183
	v_exp_f32_e32 v182, v182
	v_exp_f32_e32 v183, v183
	v_add_f32_e32 v195, 1.0, v195
	v_rcp_f32_e32 v195, v195
	v_or_b32_e32 v180, 16, v174
	v_pk_add_f32 v[182:183], v[182:183], 1.0 op_sel_hi:[1,0]
	v_ashrrev_i32_e32 v181, 31, v180
	v_rcp_f32_e32 v210, v182
	v_pk_mul_f32 v[194:195], v[182:183], v[194:195]
	v_rcp_f32_e32 v183, v183
	v_lshlrev_b64 v[180:181], 12, v[180:181]
	v_lshl_add_u64 v[180:181], s[10:11], 0, v[180:181]
	v_lshl_add_u64 v[196:197], v[180:181], 0, v[178:179]
	v_cvt_pk_bf16_f32 v180, v175, v193
	v_cvt_pk_bf16_f32 v181, v198, v199
	v_cvt_pk_bf16_f32 v182, v208, v209
	v_cvt_pk_bf16_f32 v183, v210, v183
	v_add_f32_e32 v175, v94, v142
	global_store_dwordx4 v[196:197], v[180:183], off sc1
	v_mul_f32_e32 v175, 0xbfb8aa3b, v175
	s_nop 0
	v_cvt_pk_bf16_f32 v180, v184, v185
	v_cvt_pk_bf16_f32 v181, v186, v187
	v_cvt_pk_bf16_f32 v182, v188, v189
	v_cvt_pk_bf16_f32 v183, v194, v195
	global_store_dwordx4 v[196:197], v[180:183], off offset:2048 sc1
	v_add_f32_e32 v187, v89, v141
	v_mul_f32_e32 v187, 0xbfb8aa3b, v187
	v_exp_f32_e32 v182, v175
	v_add_f32_e32 v175, v86, v138
	v_mul_f32_e32 v175, 0xbfb8aa3b, v175
	v_exp_f32_e32 v175, v175
	v_exp_f32_e32 v187, v187
	v_add_f32_e32 v189, v83, v131
	v_mul_f32_e32 v189, 0xbfb8aa3b, v189
	v_add_f32_e32 v175, 1.0, v175
	v_rcp_f32_e32 v184, v175
	v_add_f32_e32 v175, v95, v143
	v_mul_f32_e32 v175, 0xbfb8aa3b, v175
	v_exp_f32_e32 v183, v175
	v_add_f32_e32 v175, v87, v139
	v_mul_f32_e32 v175, 0xbfb8aa3b, v175
	v_exp_f32_e32 v175, v175
	v_pk_add_f32 v[182:183], v[182:183], 1.0 op_sel_hi:[1,0]
	v_add_f32_e32 v187, 1.0, v187
	v_rcp_f32_e32 v193, v183
	v_add_f32_e32 v175, 1.0, v175
	v_rcp_f32_e32 v185, v175
	v_rcp_f32_e32 v175, v182
	v_rcp_f32_e32 v187, v187
	v_exp_f32_e32 v189, v189
	v_pk_mul_f32 v[184:185], v[182:183], v[184:185]
	v_add_f32_e32 v183, v88, v140
	v_mul_f32_e32 v183, 0xbfb8aa3b, v183
	v_exp_f32_e32 v183, v183
	v_add_f32_e32 v182, v96, v144
	v_mul_f32_e32 v182, 0xbfb8aa3b, v182
	v_exp_f32_e32 v182, v182
	v_add_f32_e32 v183, 1.0, v183
	v_rcp_f32_e32 v186, v183
	v_add_f32_e32 v183, v97, v145
	v_mul_f32_e32 v183, 0xbfb8aa3b, v183
	v_exp_f32_e32 v183, v183
	v_add_f32_e32 v189, 1.0, v189
	v_rcp_f32_e32 v189, v189
	v_add_f32_e32 v195, v85, v133
	v_pk_add_f32 v[182:183], v[182:183], 1.0 op_sel_hi:[1,0]
	v_mul_f32_e32 v195, 0xbfb8aa3b, v195
	v_pk_mul_f32 v[186:187], v[182:183], v[186:187]
	v_rcp_f32_e32 v199, v183
	v_add_f32_e32 v183, v82, v130
	v_mul_f32_e32 v183, 0xbfb8aa3b, v183
	v_exp_f32_e32 v183, v183
	v_rcp_f32_e32 v198, v182
	v_add_f32_e32 v182, v90, v134
	v_mul_f32_e32 v182, 0xbfb8aa3b, v182
	v_add_f32_e32 v183, 1.0, v183
	v_rcp_f32_e32 v188, v183
	v_add_f32_e32 v183, v91, v135
	v_mul_f32_e32 v183, 0xbfb8aa3b, v183
	v_exp_f32_e32 v182, v182
	v_exp_f32_e32 v183, v183
	v_exp_f32_e32 v195, v195
	v_or_b32_e32 v180, 32, v174
	v_ashrrev_i32_e32 v181, 31, v180
	v_pk_add_f32 v[182:183], v[182:183], 1.0 op_sel_hi:[1,0]
	v_add_f32_e32 v195, 1.0, v195
	v_pk_mul_f32 v[188:189], v[182:183], v[188:189]
	v_rcp_f32_e32 v209, v183
	v_add_f32_e32 v183, v84, v132
	v_mul_f32_e32 v183, 0xbfb8aa3b, v183
	v_exp_f32_e32 v183, v183
	v_rcp_f32_e32 v208, v182
	v_add_f32_e32 v182, v92, v136
	v_mul_f32_e32 v182, 0xbfb8aa3b, v182
	v_add_f32_e32 v183, 1.0, v183
	v_rcp_f32_e32 v194, v183
	v_add_f32_e32 v183, v93, v137
	v_mul_f32_e32 v183, 0xbfb8aa3b, v183
	v_exp_f32_e32 v182, v182
	v_exp_f32_e32 v183, v183
	v_rcp_f32_e32 v195, v195
	v_lshlrev_b64 v[180:181], 12, v[180:181]
	v_lshl_add_u64 v[180:181], s[10:11], 0, v[180:181]
	v_pk_add_f32 v[182:183], v[182:183], 1.0 op_sel_hi:[1,0]
	v_lshl_add_u64 v[196:197], v[180:181], 0, v[178:179]
	v_rcp_f32_e32 v210, v182
	v_pk_mul_f32 v[194:195], v[182:183], v[194:195]
	v_rcp_f32_e32 v183, v183
	v_cvt_pk_bf16_f32 v180, v175, v193
	v_cvt_pk_bf16_f32 v181, v198, v199
	v_cvt_pk_bf16_f32 v182, v208, v209
	v_cvt_pk_bf16_f32 v183, v210, v183
	v_add_f32_e32 v175, v78, v142
	global_store_dwordx4 v[196:197], v[180:183], off sc1
	v_mul_f32_e32 v175, 0xbfb8aa3b, v175
	s_nop 0
	v_cvt_pk_bf16_f32 v180, v184, v185
	v_cvt_pk_bf16_f32 v181, v186, v187
	v_cvt_pk_bf16_f32 v182, v188, v189
	v_cvt_pk_bf16_f32 v183, v194, v195
	global_store_dwordx4 v[196:197], v[180:183], off offset:2048 sc1
	v_add_f32_e32 v187, v73, v141
	v_mul_f32_e32 v187, 0xbfb8aa3b, v187
	v_exp_f32_e32 v182, v175
	v_add_f32_e32 v175, v70, v138
	v_mul_f32_e32 v175, 0xbfb8aa3b, v175
	v_exp_f32_e32 v175, v175
	v_exp_f32_e32 v187, v187
	v_add_f32_e32 v189, v67, v131
	v_mul_f32_e32 v189, 0xbfb8aa3b, v189
	v_add_f32_e32 v175, 1.0, v175
	v_rcp_f32_e32 v184, v175
	v_add_f32_e32 v175, v79, v143
	v_mul_f32_e32 v175, 0xbfb8aa3b, v175
	v_exp_f32_e32 v183, v175
	v_add_f32_e32 v175, v71, v139
	v_mul_f32_e32 v175, 0xbfb8aa3b, v175
	v_exp_f32_e32 v175, v175
	v_pk_add_f32 v[182:183], v[182:183], 1.0 op_sel_hi:[1,0]
	v_add_f32_e32 v187, 1.0, v187
	v_rcp_f32_e32 v193, v183
	v_add_f32_e32 v175, 1.0, v175
	v_rcp_f32_e32 v185, v175
	v_rcp_f32_e32 v175, v182
	v_rcp_f32_e32 v187, v187
	v_exp_f32_e32 v189, v189
	v_pk_mul_f32 v[184:185], v[182:183], v[184:185]
	v_add_f32_e32 v183, v72, v140
	v_mul_f32_e32 v183, 0xbfb8aa3b, v183
	v_exp_f32_e32 v183, v183
	v_add_f32_e32 v182, v80, v144
	v_mul_f32_e32 v182, 0xbfb8aa3b, v182
	v_exp_f32_e32 v182, v182
	v_add_f32_e32 v183, 1.0, v183
	v_rcp_f32_e32 v186, v183
	v_add_f32_e32 v183, v81, v145
	v_mul_f32_e32 v183, 0xbfb8aa3b, v183
	v_exp_f32_e32 v183, v183
	v_add_f32_e32 v189, 1.0, v189
	v_rcp_f32_e32 v189, v189
	v_add_f32_e32 v195, v69, v133
	v_pk_add_f32 v[182:183], v[182:183], 1.0 op_sel_hi:[1,0]
	v_mul_f32_e32 v195, 0xbfb8aa3b, v195
	v_pk_mul_f32 v[186:187], v[182:183], v[186:187]
	v_rcp_f32_e32 v197, v183
	v_add_f32_e32 v183, v66, v130
	v_mul_f32_e32 v183, 0xbfb8aa3b, v183
	v_exp_f32_e32 v183, v183
	v_rcp_f32_e32 v196, v182
	v_add_f32_e32 v182, v74, v134
	v_mul_f32_e32 v182, 0xbfb8aa3b, v182
	v_add_f32_e32 v183, 1.0, v183
	v_rcp_f32_e32 v188, v183
	v_add_f32_e32 v183, v75, v135
	v_mul_f32_e32 v183, 0xbfb8aa3b, v183
	v_exp_f32_e32 v182, v182
	v_exp_f32_e32 v183, v183
	v_exp_f32_e32 v195, v195
	v_or_b32_e32 v180, 48, v174
	v_ashrrev_i32_e32 v181, 31, v180
	v_pk_add_f32 v[182:183], v[182:183], 1.0 op_sel_hi:[1,0]
	v_add_f32_e32 v195, 1.0, v195
	v_pk_mul_f32 v[188:189], v[182:183], v[188:189]
	v_rcp_f32_e32 v199, v183
	v_add_f32_e32 v183, v68, v132
	v_mul_f32_e32 v183, 0xbfb8aa3b, v183
	v_exp_f32_e32 v183, v183
	v_rcp_f32_e32 v198, v182
	v_add_f32_e32 v182, v76, v136
	v_mul_f32_e32 v182, 0xbfb8aa3b, v182
	v_add_f32_e32 v183, 1.0, v183
	v_rcp_f32_e32 v194, v183
	v_add_f32_e32 v183, v77, v137
	v_mul_f32_e32 v183, 0xbfb8aa3b, v183
	v_exp_f32_e32 v182, v182
	v_exp_f32_e32 v183, v183
	v_rcp_f32_e32 v195, v195
	v_lshlrev_b64 v[180:181], 12, v[180:181]
	v_lshl_add_u64 v[180:181], s[10:11], 0, v[180:181]
	v_pk_add_f32 v[182:183], v[182:183], 1.0 op_sel_hi:[1,0]
	s_nop 0
	v_rcp_f32_e32 v208, v182
	v_rcp_f32_e32 v209, v183
	v_pk_mul_f32 v[194:195], v[182:183], v[194:195]
	v_lshl_add_u64 v[182:183], v[180:181], 0, v[178:179]
	v_cvt_pk_bf16_f32 v178, v175, v193
	v_cvt_pk_bf16_f32 v179, v196, v197
	v_cvt_pk_bf16_f32 v180, v198, v199
	v_cvt_pk_bf16_f32 v181, v208, v209
	v_add_f32_e32 v175, v62, v142
	global_store_dwordx4 v[182:183], v[178:181], off sc1
	v_mul_f32_e32 v175, 0xbfb8aa3b, v175
	s_nop 0
	v_cvt_pk_bf16_f32 v178, v184, v185
	v_cvt_pk_bf16_f32 v179, v186, v187
	v_cvt_pk_bf16_f32 v180, v188, v189
	v_cvt_pk_bf16_f32 v181, v194, v195
	global_store_dwordx4 v[182:183], v[178:181], off offset:2048 sc1
	v_lshl_add_u64 v[194:195], v[176:177], 0, s[0:1]
	s_mov_b32 s0, 0x80000
	v_exp_f32_e32 v178, v175
	v_add_f32_e32 v175, v54, v138
	v_mul_f32_e32 v175, 0xbfb8aa3b, v175
	v_exp_f32_e32 v175, v175
	s_nop 0
	v_add_f32_e32 v175, 1.0, v175
	v_rcp_f32_e32 v180, v175
	v_add_f32_e32 v175, v63, v143
	v_mul_f32_e32 v175, 0xbfb8aa3b, v175
	v_exp_f32_e32 v179, v175
	v_add_f32_e32 v175, v55, v139
	v_mul_f32_e32 v175, 0xbfb8aa3b, v175
	v_exp_f32_e32 v175, v175
	v_pk_add_f32 v[182:183], v[178:179], 1.0 op_sel_hi:[1,0]
	v_add_f32_e32 v175, 1.0, v175
	v_rcp_f32_e32 v181, v175
	v_rcp_f32_e32 v193, v183
	v_rcp_f32_e32 v175, v182
	v_pk_mul_f32 v[178:179], v[182:183], v[180:181]
	v_add_f32_e32 v181, v56, v140
	v_mul_f32_e32 v181, 0xbfb8aa3b, v181
	v_exp_f32_e32 v181, v181
	v_add_f32_e32 v183, v57, v141
	v_mul_f32_e32 v183, 0xbfb8aa3b, v183
	v_exp_f32_e32 v183, v183
	v_add_f32_e32 v181, 1.0, v181
	v_add_f32_e32 v180, v64, v144
	v_rcp_f32_e32 v182, v181
	v_add_f32_e32 v181, v65, v145
	v_mul_f32_e32 v180, 0xbfb8aa3b, v180
	v_mul_f32_e32 v181, 0xbfb8aa3b, v181
	v_exp_f32_e32 v180, v180
	v_exp_f32_e32 v181, v181
	v_add_f32_e32 v183, 1.0, v183
	v_rcp_f32_e32 v183, v183
	v_cvt_pk_bf16_f32 v178, v178, v179
	v_pk_add_f32 v[180:181], v[180:181], 1.0 op_sel_hi:[1,0]
	s_nop 0
	v_pk_mul_f32 v[184:185], v[180:181], v[182:183]
	v_rcp_f32_e32 v197, v181
	v_add_f32_e32 v181, v50, v130
	v_mul_f32_e32 v181, 0xbfb8aa3b, v181
	v_exp_f32_e32 v181, v181
	v_add_f32_e32 v183, v51, v131
	v_mul_f32_e32 v183, 0xbfb8aa3b, v183
	v_exp_f32_e32 v183, v183
	v_add_f32_e32 v181, 1.0, v181
	v_rcp_f32_e32 v196, v180
	v_add_f32_e32 v180, v58, v134
	v_rcp_f32_e32 v182, v181
	v_add_f32_e32 v181, v59, v135
	v_mul_f32_e32 v180, 0xbfb8aa3b, v180
	v_mul_f32_e32 v181, 0xbfb8aa3b, v181
	v_exp_f32_e32 v180, v180
	v_exp_f32_e32 v181, v181
	v_add_f32_e32 v183, 1.0, v183
	v_rcp_f32_e32 v183, v183
	v_cvt_pk_bf16_f32 v179, v184, v185
	v_pk_add_f32 v[180:181], v[180:181], 1.0 op_sel_hi:[1,0]
	s_nop 0
	v_pk_mul_f32 v[186:187], v[180:181], v[182:183]
	v_rcp_f32_e32 v199, v181
	v_add_f32_e32 v181, v52, v132
	v_mul_f32_e32 v181, 0xbfb8aa3b, v181
	v_exp_f32_e32 v181, v181
	v_add_f32_e32 v183, v53, v133
	v_mul_f32_e32 v183, 0xbfb8aa3b, v183
	v_exp_f32_e32 v183, v183
	v_add_f32_e32 v181, 1.0, v181
	v_rcp_f32_e32 v198, v180
	v_add_f32_e32 v180, v60, v136
	v_rcp_f32_e32 v182, v181
	v_add_f32_e32 v181, v61, v137
	v_mul_f32_e32 v180, 0xbfb8aa3b, v180
	v_mul_f32_e32 v181, 0xbfb8aa3b, v181
	v_exp_f32_e32 v180, v180
	v_exp_f32_e32 v181, v181
	v_add_f32_e32 v183, 1.0, v183
	v_rcp_f32_e32 v183, v183
	v_pk_add_f32 v[180:181], v[180:181], 1.0 op_sel_hi:[1,0]
	s_nop 0
	v_rcp_f32_e32 v208, v180
	v_pk_mul_f32 v[188:189], v[180:181], v[182:183]
	v_rcp_f32_e32 v183, v181
	v_cvt_pk_bf16_f32 v181, v196, v197
	v_add_co_u32_e32 v196, vcc, s0, v176
	v_cvt_pk_bf16_f32 v180, v175, v193
	v_cvt_pk_bf16_f32 v182, v198, v199
	v_cvt_pk_bf16_f32 v183, v208, v183
	v_addc_co_u32_e32 v197, vcc, 0, v177, vcc
	v_add_f32_e32 v175, v46, v142
	global_store_dwordx4 v[196:197], v[180:183], off sc1
	v_mul_f32_e32 v175, 0xbfb8aa3b, v175
	s_mov_b64 s[0:1], 0x90000
	v_cvt_pk_bf16_f32 v180, v186, v187
	v_cvt_pk_bf16_f32 v181, v188, v189
	global_store_dwordx4 v[194:195], v[178:181], off offset:2048 sc1
	v_lshl_add_u64 v[194:195], v[176:177], 0, s[0:1]
	s_mov_b64 s[0:1], 0xa0000
	v_exp_f32_e32 v178, v175
	v_add_f32_e32 v175, v38, v138
	v_mul_f32_e32 v175, 0xbfb8aa3b, v175
	v_exp_f32_e32 v175, v175
	s_nop 0
	v_add_f32_e32 v175, 1.0, v175
	v_rcp_f32_e32 v180, v175
	v_add_f32_e32 v175, v47, v143
	v_mul_f32_e32 v175, 0xbfb8aa3b, v175
	v_exp_f32_e32 v179, v175
	v_add_f32_e32 v175, v39, v139
	v_mul_f32_e32 v175, 0xbfb8aa3b, v175
	v_exp_f32_e32 v175, v175
	v_pk_add_f32 v[182:183], v[178:179], 1.0 op_sel_hi:[1,0]
	v_add_f32_e32 v175, 1.0, v175
	v_rcp_f32_e32 v181, v175
	v_rcp_f32_e32 v193, v183
	v_rcp_f32_e32 v175, v182
	v_pk_mul_f32 v[178:179], v[182:183], v[180:181]
	v_add_f32_e32 v181, v40, v140
	v_mul_f32_e32 v181, 0xbfb8aa3b, v181
	v_exp_f32_e32 v181, v181
	v_add_f32_e32 v183, v41, v141
	v_mul_f32_e32 v183, 0xbfb8aa3b, v183
	v_exp_f32_e32 v183, v183
	v_add_f32_e32 v181, 1.0, v181
	v_add_f32_e32 v180, v48, v144
	v_rcp_f32_e32 v182, v181
	v_add_f32_e32 v181, v49, v145
	v_mul_f32_e32 v180, 0xbfb8aa3b, v180
	v_mul_f32_e32 v181, 0xbfb8aa3b, v181
	v_exp_f32_e32 v180, v180
	v_exp_f32_e32 v181, v181
	v_add_f32_e32 v183, 1.0, v183
	v_rcp_f32_e32 v183, v183
	v_cvt_pk_bf16_f32 v178, v178, v179
	v_pk_add_f32 v[180:181], v[180:181], 1.0 op_sel_hi:[1,0]
	s_nop 0
	v_pk_mul_f32 v[184:185], v[180:181], v[182:183]
	v_rcp_f32_e32 v197, v181
	v_add_f32_e32 v181, v34, v130
	v_mul_f32_e32 v181, 0xbfb8aa3b, v181
	v_exp_f32_e32 v181, v181
	v_add_f32_e32 v183, v35, v131
	v_mul_f32_e32 v183, 0xbfb8aa3b, v183
	v_exp_f32_e32 v183, v183
	v_add_f32_e32 v181, 1.0, v181
	v_rcp_f32_e32 v196, v180
	v_add_f32_e32 v180, v42, v134
	v_rcp_f32_e32 v182, v181
	v_add_f32_e32 v181, v43, v135
	v_mul_f32_e32 v180, 0xbfb8aa3b, v180
	v_mul_f32_e32 v181, 0xbfb8aa3b, v181
	v_exp_f32_e32 v180, v180
	v_exp_f32_e32 v181, v181
	v_add_f32_e32 v183, 1.0, v183
	v_rcp_f32_e32 v183, v183
	v_cvt_pk_bf16_f32 v179, v184, v185
	v_pk_add_f32 v[180:181], v[180:181], 1.0 op_sel_hi:[1,0]
	s_nop 0
	v_pk_mul_f32 v[186:187], v[180:181], v[182:183]
	v_rcp_f32_e32 v199, v181
	v_add_f32_e32 v181, v36, v132
	v_mul_f32_e32 v181, 0xbfb8aa3b, v181
	v_exp_f32_e32 v181, v181
	v_add_f32_e32 v183, v37, v133
	v_mul_f32_e32 v183, 0xbfb8aa3b, v183
	v_exp_f32_e32 v183, v183
	v_add_f32_e32 v181, 1.0, v181
	v_rcp_f32_e32 v198, v180
	v_add_f32_e32 v180, v44, v136
	v_rcp_f32_e32 v182, v181
	v_add_f32_e32 v181, v45, v137
	v_mul_f32_e32 v180, 0xbfb8aa3b, v180
	v_mul_f32_e32 v181, 0xbfb8aa3b, v181
	v_exp_f32_e32 v180, v180
	v_exp_f32_e32 v181, v181
	v_add_f32_e32 v183, 1.0, v183
	v_rcp_f32_e32 v183, v183
	v_pk_add_f32 v[180:181], v[180:181], 1.0 op_sel_hi:[1,0]
	s_nop 0
	v_rcp_f32_e32 v208, v180
	v_pk_mul_f32 v[188:189], v[180:181], v[182:183]
	v_rcp_f32_e32 v183, v181
	v_cvt_pk_bf16_f32 v181, v196, v197
	v_add_co_u32_e32 v196, vcc, s86, v176
	v_cvt_pk_bf16_f32 v180, v175, v193
	v_cvt_pk_bf16_f32 v182, v198, v199
	v_cvt_pk_bf16_f32 v183, v208, v183
	v_addc_co_u32_e32 v197, vcc, 0, v177, vcc
	v_add_f32_e32 v175, v30, v142
	global_store_dwordx4 v[196:197], v[180:183], off sc1
	v_mul_f32_e32 v175, 0xbfb8aa3b, v175
	v_add_f32_e32 v142, v14, v142
	v_cvt_pk_bf16_f32 v180, v186, v187
	v_cvt_pk_bf16_f32 v181, v188, v189
	global_store_dwordx4 v[194:195], v[178:181], off offset:2048 sc1
	v_mul_f32_e32 v142, 0xbfb8aa3b, v142
	v_exp_f32_e32 v142, v142
	v_exp_f32_e32 v178, v175
	v_add_f32_e32 v175, v22, v138
	v_mul_f32_e32 v175, 0xbfb8aa3b, v175
	v_exp_f32_e32 v175, v175
	v_add_f32_e32 v138, v6, v138
	v_mul_f32_e32 v138, 0xbfb8aa3b, v138
	v_exp_f32_e32 v138, v138
	v_add_f32_e32 v175, 1.0, v175
	v_rcp_f32_e32 v180, v175
	v_add_f32_e32 v175, v31, v143
	v_mul_f32_e32 v175, 0xbfb8aa3b, v175
	v_exp_f32_e32 v179, v175
	v_add_f32_e32 v175, v23, v139
	v_mul_f32_e32 v175, 0xbfb8aa3b, v175
	v_exp_f32_e32 v175, v175
	v_pk_add_f32 v[182:183], v[178:179], 1.0 op_sel_hi:[1,0]
	v_add_f32_e32 v139, v7, v139
	v_rcp_f32_e32 v193, v183
	v_add_f32_e32 v175, 1.0, v175
	v_rcp_f32_e32 v181, v175
	v_rcp_f32_e32 v175, v182
	v_mul_f32_e32 v139, 0xbfb8aa3b, v139
	v_exp_f32_e32 v139, v139
	v_pk_mul_f32 v[178:179], v[182:183], v[180:181]
	v_add_f32_e32 v181, v24, v140
	v_mul_f32_e32 v181, 0xbfb8aa3b, v181
	v_exp_f32_e32 v181, v181
	v_add_f32_e32 v183, v25, v141
	v_mul_f32_e32 v183, 0xbfb8aa3b, v183
	v_exp_f32_e32 v183, v183
	v_add_f32_e32 v181, 1.0, v181
	v_add_f32_e32 v180, v32, v144
	v_rcp_f32_e32 v182, v181
	v_add_f32_e32 v181, v33, v145
	v_mul_f32_e32 v180, 0xbfb8aa3b, v180
	v_mul_f32_e32 v181, 0xbfb8aa3b, v181
	v_exp_f32_e32 v180, v180
	v_exp_f32_e32 v181, v181
	v_add_f32_e32 v183, 1.0, v183
	v_rcp_f32_e32 v183, v183
	v_add_f32_e32 v143, v15, v143
	v_pk_add_f32 v[180:181], v[180:181], 1.0 op_sel_hi:[1,0]
	v_mul_f32_e32 v143, 0xbfb8aa3b, v143
	v_pk_mul_f32 v[184:185], v[180:181], v[182:183]
	v_rcp_f32_e32 v197, v181
	v_add_f32_e32 v181, v18, v130
	v_mul_f32_e32 v181, 0xbfb8aa3b, v181
	v_exp_f32_e32 v181, v181
	v_add_f32_e32 v183, v19, v131
	v_mul_f32_e32 v183, 0xbfb8aa3b, v183
	v_exp_f32_e32 v183, v183
	v_add_f32_e32 v181, 1.0, v181
	v_rcp_f32_e32 v196, v180
	v_add_f32_e32 v180, v26, v134
	v_rcp_f32_e32 v182, v181
	v_add_f32_e32 v181, v27, v135
	v_mul_f32_e32 v180, 0xbfb8aa3b, v180
	v_mul_f32_e32 v181, 0xbfb8aa3b, v181
	v_exp_f32_e32 v180, v180
	v_exp_f32_e32 v181, v181
	v_add_f32_e32 v183, 1.0, v183
	v_rcp_f32_e32 v183, v183
	v_add_f32_e32 v138, 1.0, v138
	v_pk_add_f32 v[180:181], v[180:181], 1.0 op_sel_hi:[1,0]
	v_exp_f32_e32 v143, v143
	v_pk_mul_f32 v[186:187], v[180:181], v[182:183]
	v_rcp_f32_e32 v199, v181
	v_add_f32_e32 v181, v20, v132
	v_mul_f32_e32 v181, 0xbfb8aa3b, v181
	v_exp_f32_e32 v181, v181
	v_add_f32_e32 v183, v21, v133
	v_mul_f32_e32 v183, 0xbfb8aa3b, v183
	v_exp_f32_e32 v183, v183
	v_add_f32_e32 v181, 1.0, v181
	v_rcp_f32_e32 v198, v180
	v_add_f32_e32 v180, v28, v136
	v_rcp_f32_e32 v182, v181
	v_add_f32_e32 v181, v29, v137
	v_mul_f32_e32 v180, 0xbfb8aa3b, v180
	v_mul_f32_e32 v181, 0xbfb8aa3b, v181
	v_exp_f32_e32 v180, v180
	v_exp_f32_e32 v181, v181
	v_add_f32_e32 v183, 1.0, v183
	v_rcp_f32_e32 v183, v183
	v_add_f32_e32 v139, 1.0, v139
	v_pk_add_f32 v[180:181], v[180:181], 1.0 op_sel_hi:[1,0]
	v_lshl_add_u64 v[194:195], v[176:177], 0, s[0:1]
	v_rcp_f32_e32 v208, v180
	v_pk_mul_f32 v[188:189], v[180:181], v[182:183]
	v_rcp_f32_e32 v183, v181
	s_mov_b32 s0, 0xa0000
	v_rcp_f32_e32 v138, v138
	v_rcp_f32_e32 v139, v139
	v_add_f32_e32 v140, v8, v140
	v_add_f32_e32 v141, v9, v141
	v_add_f32_e32 v130, v2, v130
	v_add_f32_e32 v131, v3, v131
	v_cvt_pk_bf16_f32 v181, v196, v197
	v_add_co_u32_e32 v196, vcc, s0, v176
	v_mul_f32_e32 v140, 0xbfb8aa3b, v140
	v_mul_f32_e32 v141, 0xbfb8aa3b, v141
	v_mul_f32_e32 v130, 0xbfb8aa3b, v130
	v_mul_f32_e32 v131, 0xbfb8aa3b, v131
	v_cvt_pk_bf16_f32 v180, v175, v193
	v_cvt_pk_bf16_f32 v182, v198, v199
	v_cvt_pk_bf16_f32 v183, v208, v183
	v_addc_co_u32_e32 v197, vcc, 0, v177, vcc
	v_exp_f32_e32 v140, v140
	v_exp_f32_e32 v141, v141
	v_exp_f32_e32 v130, v130
	v_exp_f32_e32 v131, v131
	global_store_dwordx4 v[196:197], v[180:183], off sc1
	v_cvt_pk_bf16_f32 v178, v178, v179
	v_cvt_pk_bf16_f32 v179, v184, v185
	v_cvt_pk_bf16_f32 v180, v186, v187
	v_cvt_pk_bf16_f32 v181, v188, v189
	v_pk_add_f32 v[142:143], v[142:143], 1.0 op_sel_hi:[1,0]
	global_store_dwordx4 v[194:195], v[178:181], off offset:2048 sc1
	v_rcp_f32_e32 v175, v142
	v_pk_mul_f32 v[138:139], v[142:143], v[138:139]
	v_rcp_f32_e32 v178, v143
	v_add_f32_e32 v142, v16, v144
	v_add_f32_e32 v143, v17, v145
	v_add_f32_e32 v134, v10, v134
	v_add_f32_e32 v135, v11, v135
	v_mul_f32_e32 v142, 0xbfb8aa3b, v142
	v_mul_f32_e32 v143, 0xbfb8aa3b, v143
	v_mul_f32_e32 v134, 0xbfb8aa3b, v134
	v_mul_f32_e32 v135, 0xbfb8aa3b, v135
	v_exp_f32_e32 v142, v142
	v_add_f32_e32 v140, 1.0, v140
	v_exp_f32_e32 v143, v143
	v_add_f32_e32 v141, 1.0, v141
	v_exp_f32_e32 v134, v134
	v_add_f32_e32 v130, 1.0, v130
	v_exp_f32_e32 v135, v135
	v_add_f32_e32 v131, 1.0, v131
	v_rcp_f32_e32 v140, v140
	v_rcp_f32_e32 v141, v141
	v_rcp_f32_e32 v130, v130
	v_rcp_f32_e32 v131, v131
	v_pk_add_f32 v[142:143], v[142:143], 1.0 op_sel_hi:[1,0]
	v_pk_add_f32 v[134:135], v[134:135], 1.0 op_sel_hi:[1,0]
	v_rcp_f32_e32 v144, v142
	v_pk_mul_f32 v[140:141], v[142:143], v[140:141]
	v_rcp_f32_e32 v145, v143
	v_pk_mul_f32 v[142:143], v[134:135], v[130:131]
	v_add_f32_e32 v131, v4, v132
	v_mul_f32_e32 v131, 0xbfb8aa3b, v131
	v_exp_f32_e32 v131, v131
	v_add_f32_e32 v133, v5, v133
	v_mul_f32_e32 v133, 0xbfb8aa3b, v133
	v_exp_f32_e32 v133, v133
	v_add_f32_e32 v131, 1.0, v131
	v_add_f32_e32 v130, v12, v136
	v_rcp_f32_e32 v132, v131
	v_add_f32_e32 v131, v13, v137
	v_mul_f32_e32 v130, 0xbfb8aa3b, v130
	v_mul_f32_e32 v131, 0xbfb8aa3b, v131
	v_exp_f32_e32 v130, v130
	v_exp_f32_e32 v131, v131
	v_add_f32_e32 v133, 1.0, v133
	v_rcp_f32_e32 v133, v133
	v_rcp_f32_e32 v179, v134
	v_pk_add_f32 v[130:131], v[130:131], 1.0 op_sel_hi:[1,0]
	v_rcp_f32_e32 v180, v135
	v_rcp_f32_e32 v181, v130
	v_pk_mul_f32 v[134:135], v[130:131], v[132:133]
	v_rcp_f32_e32 v133, v131
	s_mov_b64 s[0:1], 0xb0000
	v_lshl_add_u64 v[136:137], v[176:177], 0, s[0:1]
	s_mov_b32 s0, 0xb0000
	v_cvt_pk_bf16_f32 v131, v144, v145
	v_add_co_u32_e32 v144, vcc, s0, v176
	v_cvt_pk_bf16_f32 v130, v175, v178
	v_cvt_pk_bf16_f32 v132, v179, v180
	v_cvt_pk_bf16_f32 v133, v181, v133
	v_addc_co_u32_e32 v145, vcc, 0, v177, vcc
	global_store_dwordx4 v[144:145], v[130:133], off sc1
	s_mov_b64 s[0:1], 0
	s_nop 0
	v_cvt_pk_bf16_f32 v130, v138, v139
	v_cvt_pk_bf16_f32 v131, v140, v141
	v_cvt_pk_bf16_f32 v132, v142, v143
	v_cvt_pk_bf16_f32 v133, v134, v135
	global_store_dwordx4 v[136:137], v[130:133], off offset:2048 sc1
.LBB0_274:
	s_andn2_b64 vcc, exec, s[0:1]
	s_cbranch_vccnz .LBB0_276
	s_lshl_b32 s12, -1, s82
	s_sub_i32 s13, s20, s82
	v_bitop3_b32 v130, v1, s12, v1 bitop3:0x30
	s_lshl_b32 s0, s4, 2
	v_subrev_u32_e32 v140, s3, v174
	v_lshlrev_b32_e32 v130, s13, v130
	s_or_b32 s4, s0, s44
	v_ashrrev_i32_e32 v131, s82, v140
	v_add_u32_e32 v141, s3, v130
	s_lshl_b64 s[0:1], s[4:5], 23
	v_add_u32_e32 v130, v141, v131
	v_ashrrev_i32_e32 v131, 31, v130
	s_add_u32 s0, s96, s0
	s_addc_u32 s1, s97, s1
	v_lshlrev_b64 v[130:131], 8, v[130:131]
	v_lshl_add_u64 v[130:131], s[0:1], 0, v[130:131]
	v_lshlrev_b32_e32 v134, 1, v154
	v_mov_b32_e32 v135, v0
	v_lshl_add_u64 v[136:137], v[130:131], 0, v[134:135]
	s_mov_b64 s[38:39], 0x5000080
	s_mov_b32 s4, 0x5000000
	v_lshl_add_u64 v[138:139], v[136:137], 0, s[38:39]
	v_add_co_u32_e32 v136, vcc, s4, v136
	v_cvt_pk_bf16_f32 v130, v126, v127
	v_cvt_pk_bf16_f32 v131, v128, v129
	v_cvt_pk_bf16_f32 v132, v122, v123
	v_cvt_pk_bf16_f32 v133, v124, v125
	v_addc_co_u32_e32 v137, vcc, 0, v137, vcc
	global_store_dwordx4 v[136:137], v[130:133], off offset:128 sc1
	s_nop 1
	v_cvt_pk_bf16_f32 v130, v118, v119
	v_cvt_pk_bf16_f32 v131, v120, v121
	v_cvt_pk_bf16_f32 v132, v114, v115
	v_cvt_pk_bf16_f32 v133, v116, v117
	global_store_dwordx4 v[138:139], v[130:133], off offset:64 sc1
	s_nop 1
	v_or_b32_e32 v130, 16, v140
	v_bitop3_b32 v131, v140, s12, 16 bitop3:0x32
	v_lshlrev_b32_e32 v131, s13, v131
	v_ashrrev_i32_e32 v130, s82, v130
	v_add3_u32 v130, v130, s3, v131
	v_ashrrev_i32_e32 v131, 31, v130
	v_lshlrev_b64 v[130:131], 8, v[130:131]
	v_lshl_add_u64 v[130:131], s[0:1], 0, v[130:131]
	v_lshl_add_u64 v[136:137], v[130:131], 0, v[134:135]
	v_lshl_add_u64 v[138:139], v[136:137], 0, s[38:39]
	v_add_co_u32_e32 v136, vcc, s4, v136
	v_cvt_pk_bf16_f32 v130, v110, v111
	v_cvt_pk_bf16_f32 v131, v112, v113
	v_cvt_pk_bf16_f32 v132, v106, v107
	v_cvt_pk_bf16_f32 v133, v108, v109
	v_addc_co_u32_e32 v137, vcc, 0, v137, vcc
	global_store_dwordx4 v[136:137], v[130:133], off offset:128 sc1
	s_nop 1
	v_cvt_pk_bf16_f32 v130, v102, v103
	v_cvt_pk_bf16_f32 v131, v104, v105
	v_cvt_pk_bf16_f32 v132, v98, v99
	v_cvt_pk_bf16_f32 v133, v100, v101
	global_store_dwordx4 v[138:139], v[130:133], off offset:64 sc1
	s_nop 1
	v_or_b32_e32 v130, 32, v140
	v_bitop3_b32 v131, v140, s12, 32 bitop3:0x32
	v_lshlrev_b32_e32 v131, s13, v131
	v_ashrrev_i32_e32 v130, s82, v130
	v_add3_u32 v130, v130, s3, v131
	v_ashrrev_i32_e32 v131, 31, v130
	v_lshlrev_b64 v[130:131], 8, v[130:131]
	v_lshl_add_u64 v[130:131], s[0:1], 0, v[130:131]
	v_lshl_add_u64 v[136:137], v[130:131], 0, v[134:135]
	v_lshl_add_u64 v[138:139], v[136:137], 0, s[38:39]
	v_add_co_u32_e32 v136, vcc, s4, v136
	v_cvt_pk_bf16_f32 v130, v94, v95
	v_cvt_pk_bf16_f32 v131, v96, v97
	v_cvt_pk_bf16_f32 v132, v90, v91
	v_cvt_pk_bf16_f32 v133, v92, v93
	v_addc_co_u32_e32 v137, vcc, 0, v137, vcc
	global_store_dwordx4 v[136:137], v[130:133], off offset:128 sc1
	s_nop 1
	v_cvt_pk_bf16_f32 v130, v86, v87
	v_cvt_pk_bf16_f32 v131, v88, v89
	v_cvt_pk_bf16_f32 v132, v82, v83
	v_cvt_pk_bf16_f32 v133, v84, v85
	global_store_dwordx4 v[138:139], v[130:133], off offset:64 sc1
	s_nop 1
	v_or_b32_e32 v130, 48, v140
	v_bitop3_b32 v131, v140, s12, 48 bitop3:0x32
	v_lshlrev_b32_e32 v131, s13, v131
	v_ashrrev_i32_e32 v130, s82, v130
	v_add3_u32 v130, v130, s3, v131
	v_ashrrev_i32_e32 v131, 31, v130
	v_lshlrev_b64 v[130:131], 8, v[130:131]
	v_lshl_add_u64 v[130:131], s[0:1], 0, v[130:131]
	v_lshl_add_u64 v[136:137], v[130:131], 0, v[134:135]
	v_lshl_add_u64 v[138:139], v[136:137], 0, s[38:39]
	v_add_co_u32_e32 v136, vcc, s4, v136
	v_cvt_pk_bf16_f32 v130, v78, v79
	v_cvt_pk_bf16_f32 v131, v80, v81
	v_cvt_pk_bf16_f32 v132, v74, v75
	v_cvt_pk_bf16_f32 v133, v76, v77
	v_addc_co_u32_e32 v137, vcc, 0, v137, vcc
	global_store_dwordx4 v[136:137], v[130:133], off offset:128 sc1
	s_nop 1
	v_cvt_pk_bf16_f32 v130, v70, v71
	v_cvt_pk_bf16_f32 v131, v72, v73
	v_cvt_pk_bf16_f32 v132, v66, v67
	v_cvt_pk_bf16_f32 v133, v68, v69
	global_store_dwordx4 v[138:139], v[130:133], off offset:64 sc1
	s_nop 1
	v_add_u32_e32 v130, 0x80, v140
	v_ashrrev_i32_e32 v130, s82, v130
	v_add_u32_e32 v130, v130, v141
	v_ashrrev_i32_e32 v131, 31, v130
	v_lshlrev_b64 v[130:131], 8, v[130:131]
	v_lshl_add_u64 v[130:131], s[0:1], 0, v[130:131]
	v_lshl_add_u64 v[136:137], v[130:131], 0, v[134:135]
	v_lshl_add_u64 v[138:139], v[136:137], 0, s[38:39]
	v_add_co_u32_e32 v136, vcc, s4, v136
	v_cvt_pk_bf16_f32 v130, v62, v63
	v_cvt_pk_bf16_f32 v131, v64, v65
	v_cvt_pk_bf16_f32 v132, v58, v59
	v_cvt_pk_bf16_f32 v133, v60, v61
	v_addc_co_u32_e32 v137, vcc, 0, v137, vcc
	global_store_dwordx4 v[136:137], v[130:133], off offset:128 sc1
	s_nop 1
	v_cvt_pk_bf16_f32 v130, v54, v55
	v_cvt_pk_bf16_f32 v131, v56, v57
	v_cvt_pk_bf16_f32 v132, v50, v51
	v_cvt_pk_bf16_f32 v133, v52, v53
	global_store_dwordx4 v[138:139], v[130:133], off offset:64 sc1
	s_nop 1
	v_add_u32_e32 v130, 0x90, v140
	v_bitop3_b32 v131, v130, s12, v130 bitop3:0x30
	v_lshlrev_b32_e32 v131, s13, v131
	v_ashrrev_i32_e32 v130, s82, v130
	v_add3_u32 v130, v130, s3, v131
	v_ashrrev_i32_e32 v131, 31, v130
	v_lshlrev_b64 v[130:131], 8, v[130:131]
	v_lshl_add_u64 v[130:131], s[0:1], 0, v[130:131]
	v_lshl_add_u64 v[136:137], v[130:131], 0, v[134:135]
	v_lshl_add_u64 v[138:139], v[136:137], 0, s[38:39]
	v_add_co_u32_e32 v136, vcc, s4, v136
	v_cvt_pk_bf16_f32 v130, v46, v47
	v_cvt_pk_bf16_f32 v131, v48, v49
	v_cvt_pk_bf16_f32 v132, v42, v43
	v_cvt_pk_bf16_f32 v133, v44, v45
	v_addc_co_u32_e32 v137, vcc, 0, v137, vcc
	global_store_dwordx4 v[136:137], v[130:133], off offset:128 sc1
	s_nop 1
	v_cvt_pk_bf16_f32 v130, v38, v39
	v_cvt_pk_bf16_f32 v131, v40, v41
	v_cvt_pk_bf16_f32 v132, v34, v35
	v_cvt_pk_bf16_f32 v133, v36, v37
	global_store_dwordx4 v[138:139], v[130:133], off offset:64 sc1
	s_nop 1
	v_add_u32_e32 v130, 0xa0, v140
	v_bitop3_b32 v131, v130, s12, v130 bitop3:0x30
	v_lshlrev_b32_e32 v131, s13, v131
	v_ashrrev_i32_e32 v130, s82, v130
	v_add3_u32 v130, v130, s3, v131
	v_ashrrev_i32_e32 v131, 31, v130
	v_lshlrev_b64 v[130:131], 8, v[130:131]
	v_lshl_add_u64 v[130:131], s[0:1], 0, v[130:131]
	v_lshl_add_u64 v[136:137], v[130:131], 0, v[134:135]
	v_lshl_add_u64 v[138:139], v[136:137], 0, s[38:39]
	v_add_co_u32_e32 v136, vcc, s4, v136
	v_cvt_pk_bf16_f32 v130, v30, v31
	v_cvt_pk_bf16_f32 v131, v32, v33
	v_cvt_pk_bf16_f32 v132, v26, v27
	v_cvt_pk_bf16_f32 v133, v28, v29
	v_addc_co_u32_e32 v137, vcc, 0, v137, vcc
	global_store_dwordx4 v[136:137], v[130:133], off offset:128 sc1
	s_nop 1
	v_cvt_pk_bf16_f32 v130, v22, v23
	v_cvt_pk_bf16_f32 v131, v24, v25
	v_cvt_pk_bf16_f32 v132, v18, v19
	v_cvt_pk_bf16_f32 v133, v20, v21
	global_store_dwordx4 v[138:139], v[130:133], off offset:64 sc1
	s_nop 1
	v_add_u32_e32 v130, 0xb0, v140
	v_bitop3_b32 v131, v130, s12, v130 bitop3:0x30
	v_lshlrev_b32_e32 v131, s13, v131
	v_ashrrev_i32_e32 v130, s82, v130
	v_add3_u32 v130, v130, s3, v131
	v_ashrrev_i32_e32 v131, 31, v130
	v_lshlrev_b64 v[130:131], 8, v[130:131]
	v_lshl_add_u64 v[130:131], s[0:1], 0, v[130:131]
	v_lshl_add_u64 v[134:135], v[130:131], 0, v[134:135]
	v_lshl_add_u64 v[136:137], v[134:135], 0, s[38:39]
	v_add_co_u32_e32 v134, vcc, s4, v134
	v_cvt_pk_bf16_f32 v130, v14, v15
	v_cvt_pk_bf16_f32 v131, v16, v17
	v_cvt_pk_bf16_f32 v132, v10, v11
	v_cvt_pk_bf16_f32 v133, v12, v13
	v_addc_co_u32_e32 v135, vcc, 0, v135, vcc
	global_store_dwordx4 v[134:135], v[130:133], off offset:128 sc1
	s_nop 1
	v_cvt_pk_bf16_f32 v130, v6, v7
	v_cvt_pk_bf16_f32 v131, v8, v9
	v_cvt_pk_bf16_f32 v132, v2, v3
	v_cvt_pk_bf16_f32 v133, v4, v5
	global_store_dwordx4 v[136:137], v[130:133], off offset:64 sc1

.LBB0_283:
	s_waitcnt lgkmcnt(0)
	v_add_f32_e32 v177, v185, v186
	v_fmamk_f32 v177, v177, 0x3c800000, v201
	v_rsq_f32_e32 v186, v177
	v_cndmask_b32_e64 v188, 1.0, v205, s[38:39]
	s_waitcnt vmcnt(0)
	v_pk_mul_f32 v[144:145], v[188:189], v[144:145] op_sel_hi:[0,1]
	v_pk_mul_f32 v[142:143], v[188:189], v[142:143] op_sel_hi:[0,1]
	v_pk_mul_f32 v[140:141], v[188:189], v[140:141] op_sel_hi:[0,1]
	v_pk_mul_f32 v[138:139], v[188:189], v[138:139] op_sel_hi:[0,1]
	v_pk_mul_f32 v[128:129], v[128:129], v[186:187] op_sel_hi:[1,0]
	v_pk_mul_f32 v[126:127], v[126:127], v[186:187] op_sel_hi:[1,0]
	v_pk_mul_f32 v[124:125], v[124:125], v[186:187] op_sel_hi:[1,0]
	v_pk_mul_f32 v[122:123], v[122:123], v[186:187] op_sel_hi:[1,0]
	v_pk_mul_f32 v[136:137], v[188:189], v[136:137] op_sel_hi:[0,1]
	v_pk_mul_f32 v[134:135], v[188:189], v[134:135] op_sel_hi:[0,1]
	v_pk_mul_f32 v[132:133], v[188:189], v[132:133] op_sel_hi:[0,1]
	v_pk_mul_f32 v[130:131], v[188:189], v[130:131] op_sel_hi:[0,1]
	v_pk_mul_f32 v[128:129], v[144:145], v[128:129]
	v_pk_mul_f32 v[126:127], v[142:143], v[126:127]
	v_pk_mul_f32 v[188:189], v[140:141], v[124:125]
	v_pk_mul_f32 v[124:125], v[138:139], v[122:123]
	v_cvt_pk_bf16_f32 v122, v126, v127
	v_cvt_pk_bf16_f32 v123, v128, v129
	v_cvt_pk_bf16_f32 v124, v124, v125
	v_cvt_pk_bf16_f32 v125, v188, v189
	v_pk_mul_f32 v[120:121], v[120:121], v[186:187] op_sel_hi:[1,0]
	v_pk_mul_f32 v[118:119], v[118:119], v[186:187] op_sel_hi:[1,0]
	v_pk_mul_f32 v[116:117], v[116:117], v[186:187] op_sel_hi:[1,0]
	v_pk_mul_f32 v[114:115], v[114:115], v[186:187] op_sel_hi:[1,0]
	global_store_dwordx4 v[180:181], v[122:125], off sc1
	v_pk_mul_f32 v[120:121], v[136:137], v[120:121]
	v_pk_mul_f32 v[118:119], v[134:135], v[118:119]
	v_pk_mul_f32 v[122:123], v[132:133], v[116:117]
	v_pk_mul_f32 v[116:117], v[130:131], v[114:115]
	v_cvt_pk_bf16_f32 v114, v118, v119
	v_cvt_pk_bf16_f32 v115, v120, v121
	v_cvt_pk_bf16_f32 v116, v116, v117
	v_cvt_pk_bf16_f32 v117, v122, v123
	global_store_dwordx4 v[180:181], v[114:117], off offset:64 sc1
	s_mov_b64 s[20:21], -1
	s_andn2_b64 vcc, exec, s[12:13]
	v_mul_f32_e32 v114, v111, v111
	v_mul_f32_e32 v115, v113, v113
	v_fmac_f32_e32 v114, v110, v110
	v_fmac_f32_e32 v115, v112, v112
	v_add_f32_e32 v114, v114, v115
	v_mul_f32_e32 v115, v107, v107
	v_mul_f32_e32 v116, v109, v109
	v_fmac_f32_e32 v115, v106, v106
	v_fmac_f32_e32 v116, v108, v108
	v_add_f32_e32 v115, v115, v116
	v_add_f32_e32 v114, v115, v114
	v_mul_f32_e32 v115, v103, v103
	v_mul_f32_e32 v116, v105, v105
	v_fmac_f32_e32 v115, v102, v102
	v_fmac_f32_e32 v116, v104, v104
	v_add_f32_e32 v115, v115, v116
	v_add_f32_e32 v114, v115, v114
	v_mul_f32_e32 v115, v99, v99
	v_mul_f32_e32 v116, v101, v101
	v_fmac_f32_e32 v115, v98, v98
	v_fmac_f32_e32 v116, v100, v100
	v_add_f32_e32 v115, v115, v116
	v_add_f32_e32 v114, v115, v114
	ds_bpermute_b32 v115, v183, v114
	s_mov_b64 s[48:49], s[58:59]
	s_waitcnt lgkmcnt(0)
	v_add_f32_e32 v116, v114, v115
	ds_bpermute_b32 v117, v182, v116
	v_cndmask_b32_e64 v114, 0, 1, s[12:13]
	v_cmp_ne_u32_e64 s[38:39], 1, v114
	s_cbranch_vccnz .LBB0_285
	v_or_b32_e32 v114, 16, v175
	v_bitop3_b32 v115, v175, s4, 16 bitop3:0xc8
	v_lshlrev_b32_e32 v115, s26, v115
	v_ashrrev_i32_e32 v114, s82, v114
	v_add3_u32 v114, v114, s3, v115
	v_ashrrev_i32_e32 v115, 31, v114
	s_add_u32 s12, s98, s0
	s_addc_u32 s13, s99, s1
	v_lshlrev_b64 v[114:115], 8, v[114:115]
	v_lshl_add_u64 v[114:115], s[12:13], 0, v[114:115]
	v_mov_b32_e32 v177, v0
	v_lshl_add_u64 v[114:115], v[114:115], 0, v[176:177]
	s_mov_b64 s[20:21], 0

.LBB0_287:
	s_waitcnt lgkmcnt(0)
	v_add_f32_e32 v116, v116, v117
	v_fmamk_f32 v116, v116, 0x3c800000, v201
	v_rsq_f32_e32 v116, v116
	s_and_b64 vcc, exec, s[38:39]
	s_mov_b64 s[12:13], -1
	v_pk_mul_f32 v[112:113], v[112:113], v[116:117] op_sel_hi:[1,0]
	v_pk_mul_f32 v[110:111], v[110:111], v[116:117] op_sel_hi:[1,0]
	v_pk_mul_f32 v[108:109], v[108:109], v[116:117] op_sel_hi:[1,0]
	v_pk_mul_f32 v[106:107], v[106:107], v[116:117] op_sel_hi:[1,0]
	v_pk_mul_f32 v[112:113], v[144:145], v[112:113]
	v_pk_mul_f32 v[110:111], v[142:143], v[110:111]
	v_pk_mul_f32 v[118:119], v[140:141], v[108:109]
	v_pk_mul_f32 v[108:109], v[138:139], v[106:107]
	v_pk_mul_f32 v[102:103], v[102:103], v[116:117] op_sel_hi:[1,0]
	v_cvt_pk_bf16_f32 v106, v110, v111
	v_cvt_pk_bf16_f32 v107, v112, v113
	v_cvt_pk_bf16_f32 v108, v108, v109
	v_cvt_pk_bf16_f32 v109, v118, v119
	v_pk_mul_f32 v[102:103], v[134:135], v[102:103]
	v_pk_mul_f32 v[100:101], v[100:101], v[116:117] op_sel_hi:[1,0]
	v_pk_mul_f32 v[98:99], v[98:99], v[116:117] op_sel_hi:[1,0]
	global_store_dwordx4 v[114:115], v[106:109], off sc1
	v_pk_mul_f32 v[104:105], v[104:105], v[116:117] op_sel_hi:[1,0]
	s_nop 0
	v_pk_mul_f32 v[106:107], v[132:133], v[100:101]
	v_pk_mul_f32 v[100:101], v[130:131], v[98:99]
	v_cvt_pk_bf16_f32 v98, v102, v103
	v_mul_f32_e32 v99, v95, v95
	v_mul_f32_e32 v102, v97, v97
	v_fmac_f32_e32 v99, v94, v94
	v_fmac_f32_e32 v102, v96, v96
	v_add_f32_e32 v99, v99, v102
	v_mul_f32_e32 v102, v91, v91
	v_mul_f32_e32 v103, v93, v93
	v_fmac_f32_e32 v102, v90, v90
	v_fmac_f32_e32 v103, v92, v92
	v_add_f32_e32 v102, v102, v103
	v_add_f32_e32 v99, v102, v99
	v_mul_f32_e32 v102, v87, v87
	v_mul_f32_e32 v103, v89, v89
	v_fmac_f32_e32 v102, v86, v86
	v_fmac_f32_e32 v103, v88, v88
	v_add_f32_e32 v102, v102, v103
	v_add_f32_e32 v99, v102, v99
	v_mul_f32_e32 v102, v83, v83
	v_mul_f32_e32 v103, v85, v85
	v_fmac_f32_e32 v102, v82, v82
	v_fmac_f32_e32 v103, v84, v84
	v_add_f32_e32 v102, v102, v103
	v_add_f32_e32 v102, v102, v99
	ds_bpermute_b32 v103, v183, v102
	v_pk_mul_f32 v[104:105], v[136:137], v[104:105]
	v_cvt_pk_bf16_f32 v100, v100, v101
	v_cvt_pk_bf16_f32 v99, v104, v105
	v_cvt_pk_bf16_f32 v101, v106, v107
	global_store_dwordx4 v[114:115], v[98:101], off offset:64 sc1
	s_waitcnt lgkmcnt(0)
	s_nop 0
	v_add_f32_e32 v100, v102, v103
	ds_bpermute_b32 v101, v182, v100
	s_cbranch_vccnz .LBB0_289
	v_or_b32_e32 v98, 32, v175
	v_bitop3_b32 v99, v175, s4, 32 bitop3:0xc8
	v_lshlrev_b32_e32 v99, s26, v99
	v_ashrrev_i32_e32 v98, s82, v98
	v_add3_u32 v98, v98, s3, v99
	v_ashrrev_i32_e32 v99, 31, v98
	s_add_u32 s12, s98, s0
	s_addc_u32 s13, s99, s1
	v_lshlrev_b64 v[98:99], 8, v[98:99]
	v_lshl_add_u64 v[98:99], s[12:13], 0, v[98:99]
	v_mov_b32_e32 v177, v0
	v_lshl_add_u64 v[98:99], v[98:99], 0, v[176:177]
	s_mov_b64 s[12:13], 0

.LBB0_291:
	s_waitcnt lgkmcnt(0)
	v_add_f32_e32 v100, v100, v101
	v_fmamk_f32 v100, v100, 0x3c800000, v201
	v_rsq_f32_e32 v100, v100
	s_and_b64 vcc, exec, s[38:39]
	s_mov_b64 s[12:13], -1
	v_pk_mul_f32 v[96:97], v[96:97], v[100:101] op_sel_hi:[1,0]
	v_pk_mul_f32 v[94:95], v[94:95], v[100:101] op_sel_hi:[1,0]
	v_pk_mul_f32 v[92:93], v[92:93], v[100:101] op_sel_hi:[1,0]
	v_pk_mul_f32 v[90:91], v[90:91], v[100:101] op_sel_hi:[1,0]
	v_pk_mul_f32 v[96:97], v[144:145], v[96:97]
	v_pk_mul_f32 v[94:95], v[142:143], v[94:95]
	v_pk_mul_f32 v[102:103], v[140:141], v[92:93]
	v_pk_mul_f32 v[92:93], v[138:139], v[90:91]
	v_pk_mul_f32 v[86:87], v[86:87], v[100:101] op_sel_hi:[1,0]
	v_cvt_pk_bf16_f32 v90, v94, v95
	v_cvt_pk_bf16_f32 v91, v96, v97
	v_cvt_pk_bf16_f32 v92, v92, v93
	v_cvt_pk_bf16_f32 v93, v102, v103
	v_pk_mul_f32 v[86:87], v[134:135], v[86:87]
	v_pk_mul_f32 v[84:85], v[84:85], v[100:101] op_sel_hi:[1,0]
	v_pk_mul_f32 v[82:83], v[82:83], v[100:101] op_sel_hi:[1,0]
	global_store_dwordx4 v[98:99], v[90:93], off sc1
	v_pk_mul_f32 v[88:89], v[88:89], v[100:101] op_sel_hi:[1,0]
	s_nop 0
	v_pk_mul_f32 v[90:91], v[132:133], v[84:85]
	v_pk_mul_f32 v[84:85], v[130:131], v[82:83]
	v_cvt_pk_bf16_f32 v82, v86, v87
	v_mul_f32_e32 v83, v79, v79
	v_mul_f32_e32 v86, v81, v81
	v_fmac_f32_e32 v83, v78, v78
	v_fmac_f32_e32 v86, v80, v80
	v_add_f32_e32 v83, v83, v86
	v_mul_f32_e32 v86, v75, v75
	v_mul_f32_e32 v87, v77, v77
	v_fmac_f32_e32 v86, v74, v74
	v_fmac_f32_e32 v87, v76, v76
	v_add_f32_e32 v86, v86, v87
	v_add_f32_e32 v83, v86, v83
	v_mul_f32_e32 v86, v71, v71
	v_mul_f32_e32 v87, v73, v73
	v_fmac_f32_e32 v86, v70, v70
	v_fmac_f32_e32 v87, v72, v72
	v_add_f32_e32 v86, v86, v87
	v_add_f32_e32 v83, v86, v83
	v_mul_f32_e32 v86, v67, v67
	v_mul_f32_e32 v87, v69, v69
	v_fmac_f32_e32 v86, v66, v66
	v_fmac_f32_e32 v87, v68, v68
	v_add_f32_e32 v86, v86, v87
	v_add_f32_e32 v86, v86, v83
	ds_bpermute_b32 v87, v183, v86
	v_pk_mul_f32 v[88:89], v[136:137], v[88:89]
	v_cvt_pk_bf16_f32 v84, v84, v85
	v_cvt_pk_bf16_f32 v83, v88, v89
	v_cvt_pk_bf16_f32 v85, v90, v91
	global_store_dwordx4 v[98:99], v[82:85], off offset:64 sc1
	s_waitcnt lgkmcnt(0)
	s_nop 0
	v_add_f32_e32 v84, v86, v87
	ds_bpermute_b32 v85, v182, v84
	s_cbranch_vccnz .LBB0_293
	v_or_b32_e32 v82, 48, v175
	v_bitop3_b32 v83, v175, s4, 48 bitop3:0xc8
	v_lshlrev_b32_e32 v83, s26, v83
	v_ashrrev_i32_e32 v82, s82, v82
	v_add3_u32 v82, v82, s3, v83
	v_ashrrev_i32_e32 v83, 31, v82
	s_add_u32 s12, s98, s0
	s_addc_u32 s13, s99, s1
	v_lshlrev_b64 v[82:83], 8, v[82:83]
	v_lshl_add_u64 v[82:83], s[12:13], 0, v[82:83]
	v_mov_b32_e32 v177, v0
	v_lshl_add_u64 v[82:83], v[82:83], 0, v[176:177]
	s_mov_b64 s[12:13], 0

.LBB0_295:
	s_waitcnt lgkmcnt(0)
	v_add_f32_e32 v84, v84, v85
	v_fmamk_f32 v84, v84, 0x3c800000, v201
	v_rsq_f32_e32 v84, v84
	s_and_b64 vcc, exec, s[38:39]
	s_mov_b64 s[12:13], -1
	v_pk_mul_f32 v[80:81], v[80:81], v[84:85] op_sel_hi:[1,0]
	v_pk_mul_f32 v[78:79], v[78:79], v[84:85] op_sel_hi:[1,0]
	v_pk_mul_f32 v[76:77], v[76:77], v[84:85] op_sel_hi:[1,0]
	v_pk_mul_f32 v[74:75], v[74:75], v[84:85] op_sel_hi:[1,0]
	v_pk_mul_f32 v[80:81], v[144:145], v[80:81]
	v_pk_mul_f32 v[78:79], v[142:143], v[78:79]
	v_pk_mul_f32 v[86:87], v[140:141], v[76:77]
	v_pk_mul_f32 v[76:77], v[138:139], v[74:75]
	v_pk_mul_f32 v[70:71], v[70:71], v[84:85] op_sel_hi:[1,0]
	v_cvt_pk_bf16_f32 v74, v78, v79
	v_cvt_pk_bf16_f32 v75, v80, v81
	v_cvt_pk_bf16_f32 v76, v76, v77
	v_cvt_pk_bf16_f32 v77, v86, v87
	v_pk_mul_f32 v[70:71], v[134:135], v[70:71]
	v_pk_mul_f32 v[68:69], v[68:69], v[84:85] op_sel_hi:[1,0]
	v_pk_mul_f32 v[66:67], v[66:67], v[84:85] op_sel_hi:[1,0]
	global_store_dwordx4 v[82:83], v[74:77], off sc1
	v_pk_mul_f32 v[72:73], v[72:73], v[84:85] op_sel_hi:[1,0]
	s_nop 0
	v_pk_mul_f32 v[74:75], v[132:133], v[68:69]
	v_pk_mul_f32 v[68:69], v[130:131], v[66:67]
	v_cvt_pk_bf16_f32 v66, v70, v71
	v_mul_f32_e32 v67, v63, v63
	v_mul_f32_e32 v70, v65, v65
	v_fmac_f32_e32 v67, v62, v62
	v_fmac_f32_e32 v70, v64, v64
	v_add_f32_e32 v67, v67, v70
	v_mul_f32_e32 v70, v59, v59
	v_mul_f32_e32 v71, v61, v61
	v_fmac_f32_e32 v70, v58, v58
	v_fmac_f32_e32 v71, v60, v60
	v_add_f32_e32 v70, v70, v71
	v_add_f32_e32 v67, v70, v67
	v_mul_f32_e32 v70, v55, v55
	v_mul_f32_e32 v71, v57, v57
	v_fmac_f32_e32 v70, v54, v54
	v_fmac_f32_e32 v71, v56, v56
	v_add_f32_e32 v70, v70, v71
	v_add_f32_e32 v67, v70, v67
	v_mul_f32_e32 v70, v51, v51
	v_mul_f32_e32 v71, v53, v53
	v_fmac_f32_e32 v70, v50, v50
	v_fmac_f32_e32 v71, v52, v52
	v_add_f32_e32 v70, v70, v71
	v_add_f32_e32 v70, v70, v67
	ds_bpermute_b32 v71, v183, v70
	v_pk_mul_f32 v[72:73], v[136:137], v[72:73]
	v_cvt_pk_bf16_f32 v68, v68, v69
	v_cvt_pk_bf16_f32 v67, v72, v73
	v_cvt_pk_bf16_f32 v69, v74, v75
	global_store_dwordx4 v[82:83], v[66:69], off offset:64 sc1
	s_waitcnt lgkmcnt(0)
	s_nop 0
	v_add_f32_e32 v68, v70, v71
	ds_bpermute_b32 v69, v182, v68
	s_cbranch_vccnz .LBB0_297
	v_add_u32_e32 v66, 0x80, v175
	v_ashrrev_i32_e32 v66, s82, v66
	v_add3_u32 v66, v184, s3, v66
	v_ashrrev_i32_e32 v67, 31, v66
	s_add_u32 s12, s98, s0
	s_addc_u32 s13, s99, s1
	v_lshlrev_b64 v[66:67], 8, v[66:67]
	v_lshl_add_u64 v[66:67], s[12:13], 0, v[66:67]
	v_mov_b32_e32 v177, v0
	v_lshl_add_u64 v[66:67], v[66:67], 0, v[176:177]
	s_mov_b64 s[12:13], 0

.LBB0_299:
	s_waitcnt lgkmcnt(0)
	v_add_f32_e32 v68, v68, v69
	v_fmamk_f32 v68, v68, 0x3c800000, v201
	v_rsq_f32_e32 v68, v68
	s_and_b64 vcc, exec, s[38:39]
	s_mov_b64 s[12:13], -1
	v_pk_mul_f32 v[64:65], v[64:65], v[68:69] op_sel_hi:[1,0]
	v_pk_mul_f32 v[62:63], v[62:63], v[68:69] op_sel_hi:[1,0]
	v_pk_mul_f32 v[60:61], v[60:61], v[68:69] op_sel_hi:[1,0]
	v_pk_mul_f32 v[58:59], v[58:59], v[68:69] op_sel_hi:[1,0]
	v_pk_mul_f32 v[64:65], v[144:145], v[64:65]
	v_pk_mul_f32 v[62:63], v[142:143], v[62:63]
	v_pk_mul_f32 v[70:71], v[140:141], v[60:61]
	v_pk_mul_f32 v[60:61], v[138:139], v[58:59]
	v_pk_mul_f32 v[54:55], v[54:55], v[68:69] op_sel_hi:[1,0]
	v_cvt_pk_bf16_f32 v58, v62, v63
	v_cvt_pk_bf16_f32 v59, v64, v65
	v_cvt_pk_bf16_f32 v60, v60, v61
	v_cvt_pk_bf16_f32 v61, v70, v71
	v_pk_mul_f32 v[54:55], v[134:135], v[54:55]
	v_pk_mul_f32 v[52:53], v[52:53], v[68:69] op_sel_hi:[1,0]
	v_pk_mul_f32 v[50:51], v[50:51], v[68:69] op_sel_hi:[1,0]
	global_store_dwordx4 v[66:67], v[58:61], off sc1
	v_pk_mul_f32 v[56:57], v[56:57], v[68:69] op_sel_hi:[1,0]
	s_nop 0
	v_pk_mul_f32 v[58:59], v[132:133], v[52:53]
	v_pk_mul_f32 v[52:53], v[130:131], v[50:51]
	v_cvt_pk_bf16_f32 v50, v54, v55
	v_mul_f32_e32 v51, v47, v47
	v_mul_f32_e32 v54, v49, v49
	v_fmac_f32_e32 v51, v46, v46
	v_fmac_f32_e32 v54, v48, v48
	v_add_f32_e32 v51, v51, v54
	v_mul_f32_e32 v54, v43, v43
	v_mul_f32_e32 v55, v45, v45
	v_fmac_f32_e32 v54, v42, v42
	v_fmac_f32_e32 v55, v44, v44
	v_add_f32_e32 v54, v54, v55
	v_add_f32_e32 v51, v54, v51
	v_mul_f32_e32 v54, v39, v39
	v_mul_f32_e32 v55, v41, v41
	v_fmac_f32_e32 v54, v38, v38
	v_fmac_f32_e32 v55, v40, v40
	v_add_f32_e32 v54, v54, v55
	v_add_f32_e32 v51, v54, v51
	v_mul_f32_e32 v54, v35, v35
	v_mul_f32_e32 v55, v37, v37
	v_fmac_f32_e32 v54, v34, v34
	v_fmac_f32_e32 v55, v36, v36
	v_add_f32_e32 v54, v54, v55
	v_add_f32_e32 v54, v54, v51
	ds_bpermute_b32 v55, v183, v54
	v_pk_mul_f32 v[56:57], v[136:137], v[56:57]
	v_cvt_pk_bf16_f32 v52, v52, v53
	v_cvt_pk_bf16_f32 v51, v56, v57
	v_cvt_pk_bf16_f32 v53, v58, v59
	global_store_dwordx4 v[66:67], v[50:53], off offset:64 sc1
	s_waitcnt lgkmcnt(0)
	s_nop 0
	v_add_f32_e32 v52, v54, v55
	ds_bpermute_b32 v53, v182, v52
	s_cbranch_vccnz .LBB0_301
	v_add_u32_e32 v50, 0x90, v175
	v_and_b32_e32 v51, s4, v50
	v_lshlrev_b32_e32 v51, s26, v51
	v_ashrrev_i32_e32 v50, s82, v50
	v_add3_u32 v50, v50, s3, v51
	v_ashrrev_i32_e32 v51, 31, v50
	s_add_u32 s12, s98, s0
	s_addc_u32 s13, s99, s1
	v_lshlrev_b64 v[50:51], 8, v[50:51]
	v_lshl_add_u64 v[50:51], s[12:13], 0, v[50:51]
	v_mov_b32_e32 v177, v0
	v_lshl_add_u64 v[50:51], v[50:51], 0, v[176:177]
	s_mov_b64 s[12:13], 0

.LBB0_303:
	s_waitcnt lgkmcnt(0)
	v_add_f32_e32 v52, v52, v53
	v_fmamk_f32 v52, v52, 0x3c800000, v201
	v_rsq_f32_e32 v52, v52
	s_and_b64 vcc, exec, s[38:39]
	s_mov_b64 s[12:13], -1
	v_pk_mul_f32 v[48:49], v[48:49], v[52:53] op_sel_hi:[1,0]
	v_pk_mul_f32 v[46:47], v[46:47], v[52:53] op_sel_hi:[1,0]
	v_pk_mul_f32 v[44:45], v[44:45], v[52:53] op_sel_hi:[1,0]
	v_pk_mul_f32 v[42:43], v[42:43], v[52:53] op_sel_hi:[1,0]
	v_pk_mul_f32 v[48:49], v[144:145], v[48:49]
	v_pk_mul_f32 v[46:47], v[142:143], v[46:47]
	v_pk_mul_f32 v[54:55], v[140:141], v[44:45]
	v_pk_mul_f32 v[44:45], v[138:139], v[42:43]
	v_pk_mul_f32 v[38:39], v[38:39], v[52:53] op_sel_hi:[1,0]
	v_cvt_pk_bf16_f32 v42, v46, v47
	v_cvt_pk_bf16_f32 v43, v48, v49
	v_cvt_pk_bf16_f32 v44, v44, v45
	v_cvt_pk_bf16_f32 v45, v54, v55
	v_pk_mul_f32 v[38:39], v[134:135], v[38:39]
	v_pk_mul_f32 v[36:37], v[36:37], v[52:53] op_sel_hi:[1,0]
	v_pk_mul_f32 v[34:35], v[34:35], v[52:53] op_sel_hi:[1,0]
	global_store_dwordx4 v[50:51], v[42:45], off sc1
	v_pk_mul_f32 v[40:41], v[40:41], v[52:53] op_sel_hi:[1,0]
	s_nop 0
	v_pk_mul_f32 v[42:43], v[132:133], v[36:37]
	v_pk_mul_f32 v[36:37], v[130:131], v[34:35]
	v_cvt_pk_bf16_f32 v34, v38, v39
	v_mul_f32_e32 v35, v31, v31
	v_mul_f32_e32 v38, v33, v33
	v_fmac_f32_e32 v35, v30, v30
	v_fmac_f32_e32 v38, v32, v32
	v_add_f32_e32 v35, v35, v38
	v_mul_f32_e32 v38, v27, v27
	v_mul_f32_e32 v39, v29, v29
	v_fmac_f32_e32 v38, v26, v26
	v_fmac_f32_e32 v39, v28, v28
	v_add_f32_e32 v38, v38, v39
	v_add_f32_e32 v35, v38, v35
	v_mul_f32_e32 v38, v23, v23
	v_mul_f32_e32 v39, v25, v25
	v_fmac_f32_e32 v38, v22, v22
	v_fmac_f32_e32 v39, v24, v24
	v_add_f32_e32 v38, v38, v39
	v_add_f32_e32 v35, v38, v35
	v_mul_f32_e32 v38, v19, v19
	v_mul_f32_e32 v39, v21, v21
	v_fmac_f32_e32 v38, v18, v18
	v_fmac_f32_e32 v39, v20, v20
	v_add_f32_e32 v38, v38, v39
	v_add_f32_e32 v38, v38, v35
	ds_bpermute_b32 v39, v183, v38
	v_pk_mul_f32 v[40:41], v[136:137], v[40:41]
	v_cvt_pk_bf16_f32 v36, v36, v37
	v_cvt_pk_bf16_f32 v35, v40, v41
	v_cvt_pk_bf16_f32 v37, v42, v43
	global_store_dwordx4 v[50:51], v[34:37], off offset:64 sc1
	s_waitcnt lgkmcnt(0)
	s_nop 0
	v_add_f32_e32 v36, v38, v39
	ds_bpermute_b32 v37, v182, v36
	s_cbranch_vccnz .LBB0_305
	v_add_u32_e32 v34, 0xa0, v175
	v_and_b32_e32 v35, s4, v34
	v_lshlrev_b32_e32 v35, s26, v35
	v_ashrrev_i32_e32 v34, s82, v34
	v_add3_u32 v34, v34, s3, v35
	v_ashrrev_i32_e32 v35, 31, v34
	s_add_u32 s12, s98, s0
	s_addc_u32 s13, s99, s1
	v_lshlrev_b64 v[34:35], 8, v[34:35]
	v_lshl_add_u64 v[34:35], s[12:13], 0, v[34:35]
	v_mov_b32_e32 v177, v0
	v_lshl_add_u64 v[34:35], v[34:35], 0, v[176:177]
	s_mov_b64 s[12:13], 0

.LBB0_307:
	s_waitcnt lgkmcnt(0)
	v_add_f32_e32 v36, v36, v37
	v_fmamk_f32 v36, v36, 0x3c800000, v201
	v_rsq_f32_e32 v36, v36
	s_and_b64 vcc, exec, s[38:39]
	s_mov_b64 s[12:13], -1
	v_pk_mul_f32 v[32:33], v[32:33], v[36:37] op_sel_hi:[1,0]
	v_pk_mul_f32 v[30:31], v[30:31], v[36:37] op_sel_hi:[1,0]
	v_pk_mul_f32 v[28:29], v[28:29], v[36:37] op_sel_hi:[1,0]
	v_pk_mul_f32 v[26:27], v[26:27], v[36:37] op_sel_hi:[1,0]
	v_pk_mul_f32 v[32:33], v[144:145], v[32:33]
	v_pk_mul_f32 v[30:31], v[142:143], v[30:31]
	v_pk_mul_f32 v[38:39], v[140:141], v[28:29]
	v_pk_mul_f32 v[28:29], v[138:139], v[26:27]
	v_pk_mul_f32 v[22:23], v[22:23], v[36:37] op_sel_hi:[1,0]
	v_cvt_pk_bf16_f32 v26, v30, v31
	v_cvt_pk_bf16_f32 v27, v32, v33
	v_cvt_pk_bf16_f32 v28, v28, v29
	v_cvt_pk_bf16_f32 v29, v38, v39
	v_pk_mul_f32 v[22:23], v[134:135], v[22:23]
	v_pk_mul_f32 v[20:21], v[20:21], v[36:37] op_sel_hi:[1,0]
	v_pk_mul_f32 v[18:19], v[18:19], v[36:37] op_sel_hi:[1,0]
	global_store_dwordx4 v[34:35], v[26:29], off sc1
	v_pk_mul_f32 v[24:25], v[24:25], v[36:37] op_sel_hi:[1,0]
	s_nop 0
	v_pk_mul_f32 v[26:27], v[132:133], v[20:21]
	v_pk_mul_f32 v[20:21], v[130:131], v[18:19]
	v_cvt_pk_bf16_f32 v18, v22, v23
	v_mul_f32_e32 v19, v15, v15
	v_mul_f32_e32 v22, v17, v17
	v_fmac_f32_e32 v19, v14, v14
	v_fmac_f32_e32 v22, v16, v16
	v_add_f32_e32 v19, v19, v22
	v_mul_f32_e32 v22, v11, v11
	v_mul_f32_e32 v23, v13, v13
	v_fmac_f32_e32 v22, v10, v10
	v_fmac_f32_e32 v23, v12, v12
	v_add_f32_e32 v22, v22, v23
	v_add_f32_e32 v19, v22, v19
	v_mul_f32_e32 v22, v7, v7
	v_mul_f32_e32 v23, v9, v9
	v_fmac_f32_e32 v22, v6, v6
	v_fmac_f32_e32 v23, v8, v8
	v_add_f32_e32 v22, v22, v23
	v_add_f32_e32 v19, v22, v19
	v_mul_f32_e32 v22, v3, v3
	v_mul_f32_e32 v23, v5, v5
	v_fmac_f32_e32 v22, v2, v2
	v_fmac_f32_e32 v23, v4, v4
	v_add_f32_e32 v22, v22, v23
	v_add_f32_e32 v22, v22, v19
	ds_bpermute_b32 v23, v183, v22
	v_pk_mul_f32 v[24:25], v[136:137], v[24:25]
	v_cvt_pk_bf16_f32 v20, v20, v21
	v_cvt_pk_bf16_f32 v19, v24, v25
	v_cvt_pk_bf16_f32 v21, v26, v27
	global_store_dwordx4 v[34:35], v[18:21], off offset:64 sc1
	s_waitcnt lgkmcnt(0)
	s_nop 0
	v_add_f32_e32 v20, v22, v23
	ds_bpermute_b32 v21, v182, v20
	s_cbranch_vccnz .LBB0_309
	v_add_u32_e32 v18, 0xb0, v175
	v_and_b32_e32 v19, s4, v18
	v_lshlrev_b32_e32 v19, s26, v19
	v_ashrrev_i32_e32 v18, s82, v18
	v_add3_u32 v18, v18, s3, v19
	v_ashrrev_i32_e32 v19, 31, v18
	s_add_u32 s0, s98, s0
	s_addc_u32 s1, s99, s1
	v_lshlrev_b64 v[18:19], 8, v[18:19]
	v_lshl_add_u64 v[18:19], s[0:1], 0, v[18:19]
	v_mov_b32_e32 v177, v0
	v_lshl_add_u64 v[18:19], v[18:19], 0, v[176:177]
	s_mov_b64 s[12:13], 0

.LBB0_311:
	s_waitcnt lgkmcnt(0)
	v_add_f32_e32 v20, v20, v21
	v_fmamk_f32 v20, v20, 0x3c800000, v201
	v_rsq_f32_e32 v20, v20
	s_nop 0
	v_pk_mul_f32 v[16:17], v[16:17], v[20:21] op_sel_hi:[1,0]
	v_pk_mul_f32 v[14:15], v[14:15], v[20:21] op_sel_hi:[1,0]
	v_pk_mul_f32 v[12:13], v[12:13], v[20:21] op_sel_hi:[1,0]
	v_pk_mul_f32 v[10:11], v[10:11], v[20:21] op_sel_hi:[1,0]
	v_pk_mul_f32 v[16:17], v[144:145], v[16:17]
	v_pk_mul_f32 v[14:15], v[142:143], v[14:15]
	v_pk_mul_f32 v[22:23], v[140:141], v[12:13]
	v_pk_mul_f32 v[12:13], v[138:139], v[10:11]
	v_cvt_pk_bf16_f32 v10, v14, v15
	v_cvt_pk_bf16_f32 v11, v16, v17
	v_cvt_pk_bf16_f32 v12, v12, v13
	v_cvt_pk_bf16_f32 v13, v22, v23
	v_pk_mul_f32 v[8:9], v[8:9], v[20:21] op_sel_hi:[1,0]
	v_pk_mul_f32 v[6:7], v[6:7], v[20:21] op_sel_hi:[1,0]
	v_pk_mul_f32 v[4:5], v[4:5], v[20:21] op_sel_hi:[1,0]
	v_pk_mul_f32 v[2:3], v[2:3], v[20:21] op_sel_hi:[1,0]
	global_store_dwordx4 v[18:19], v[10:13], off sc1
	v_pk_mul_f32 v[8:9], v[136:137], v[8:9]
	v_pk_mul_f32 v[6:7], v[134:135], v[6:7]
	v_pk_mul_f32 v[10:11], v[132:133], v[4:5]
	v_pk_mul_f32 v[4:5], v[130:131], v[2:3]
	v_cvt_pk_bf16_f32 v2, v6, v7
	v_cvt_pk_bf16_f32 v3, v8, v9
	v_cvt_pk_bf16_f32 v4, v4, v5
	v_cvt_pk_bf16_f32 v5, v10, v11
	global_store_dwordx4 v[18:19], v[2:5], off offset:64 sc1
	s_and_b64 vcc, exec, s[36:37]
	s_mov_b64 s[0:1], -1
	s_cbranch_vccnz .LBB0_259
